# attention prologue: lambda dot-product loop unrolled x2 with the next 8 loads in flight
# speedup vs baseline: 1.0040x; 1.0018x over previous
.LBB0_475:
	s_or_b64 exec, exec, s[6:7]
	s_mov_b64 s[8:9], -1
	s_and_b64 vcc, exec, s[90:91]
	s_waitcnt lgkmcnt(0)
	s_barrier
	s_cbranch_vccz .LBB0_531
	s_mov_b64 s[6:7], s[94:95]
	s_load_dwordx8 s[12:19], s[6:7], 0x98
	s_load_dwordx2 s[8:9], s[6:7], 0xb8
	s_nop 0
	s_load_dwordx2 s[6:7], s[6:7], 0xd0
	s_lshl_b64 s[10:11], s[76:77], 7
	s_and_b32 s10, s10, 0xffffff00
	s_waitcnt lgkmcnt(0)
	s_add_u32 s12, s12, s10
	s_addc_u32 s13, s13, s11
	s_add_u32 s14, s14, s10
	s_addc_u32 s15, s15, s11
	s_add_u32 s16, s16, s10
	s_addc_u32 s17, s17, s11
	v_mov_b32_e32 v2, v214
	s_add_u32 s18, s18, s10
	s_addc_u32 s19, s19, s11
	v_readfirstlane_b32 s24, v2
	s_mov_b64 s[10:11], 0
	v_mov_b32_e32 v1, 0
	v_mov_b32_e32 v0, 0
	s_add_u32 s20, s12, s10
	s_addc_u32 s21, s13, s11
	global_load_dwordx4 v[4:7], v173, s[20:21] offset:16
	global_load_dwordx4 v[8:11], v173, s[20:21]
	s_add_u32 s20, s14, s10
	s_addc_u32 s21, s15, s11
	global_load_dwordx4 v[12:15], v173, s[20:21] offset:16
	global_load_dwordx4 v[16:19], v173, s[20:21]
	s_add_u32 s20, s16, s10
	s_addc_u32 s21, s17, s11
	global_load_dwordx4 v[20:23], v173, s[20:21] offset:16
	global_load_dwordx4 v[24:27], v173, s[20:21]
	s_add_u32 s20, s18, s10
	s_addc_u32 s21, s19, s11
	global_load_dwordx4 v[28:31], v173, s[20:21] offset:16
	global_load_dwordx4 v[32:35], v173, s[20:21]
	s_add_u32 s10, s10, 32
	s_addc_u32 s11, s11, 0
.LBB0_477:
	s_add_u32 s20, s12, s10
	s_addc_u32 s21, s13, s11
	global_load_dwordx4 v[40:43], v173, s[20:21] offset:16
	global_load_dwordx4 v[44:47], v173, s[20:21]
	s_add_u32 s20, s14, s10
	s_addc_u32 s21, s15, s11
	global_load_dwordx4 v[48:51], v173, s[20:21] offset:16
	global_load_dwordx4 v[52:55], v173, s[20:21]
	s_add_u32 s20, s16, s10
	s_addc_u32 s21, s17, s11
	global_load_dwordx4 v[56:59], v173, s[20:21] offset:16
	global_load_dwordx4 v[60:63], v173, s[20:21]
	s_add_u32 s20, s18, s10
	s_addc_u32 s21, s19, s11
	global_load_dwordx4 v[64:67], v173, s[20:21] offset:16
	global_load_dwordx4 v[68:71], v173, s[20:21]
	s_add_u32 s10, s10, 32
	s_addc_u32 s11, s11, 0
	s_waitcnt vmcnt(8)
	v_mov_b32_e32 v36, v8
	v_mov_b32_e32 v8, v10
	v_mov_b32_e32 v10, v12
	v_mov_b32_e32 v38, v16
	v_mov_b32_e32 v16, v18
	v_mov_b32_e32 v37, v24
	v_mov_b32_e32 v24, v9
	v_mov_b32_e32 v9, v26
	v_mov_b32_e32 v39, v32
	v_pk_fma_f32 v[0:1], v[36:37], v[38:39], v[0:1]
	v_mov_b32_e32 v32, v17
	v_pk_fma_f32 v[0:1], v[24:25], v[32:33], v[0:1]
	v_mov_b32_e32 v17, v34
	v_pk_fma_f32 v[0:1], v[8:9], v[16:17], v[0:1]
	v_mov_b32_e32 v26, v11
	v_mov_b32_e32 v34, v19
	v_pk_fma_f32 v[0:1], v[26:27], v[34:35], v[0:1]
	v_mov_b32_e32 v8, v4
	v_mov_b32_e32 v9, v20
	v_mov_b32_e32 v11, v28
	v_pk_fma_f32 v[0:1], v[8:9], v[10:11], v[0:1]
	v_mov_b32_e32 v20, v5
	v_mov_b32_e32 v28, v13
	v_pk_fma_f32 v[0:1], v[20:21], v[28:29], v[0:1]
	v_mov_b32_e32 v4, v6
	v_mov_b32_e32 v5, v22
	v_mov_b32_e32 v8, v14
	v_mov_b32_e32 v9, v30
	v_pk_fma_f32 v[0:1], v[4:5], v[8:9], v[0:1]
	v_mov_b32_e32 v22, v7
	v_mov_b32_e32 v30, v15
	v_pk_fma_f32 v[0:1], v[22:23], v[30:31], v[0:1]
	s_cmpk_lt_u32 s10, 0x100
	s_cbranch_scc0 .Llam_last
	s_add_u32 s20, s12, s10
	s_addc_u32 s21, s13, s11
	global_load_dwordx4 v[4:7], v173, s[20:21] offset:16
	global_load_dwordx4 v[8:11], v173, s[20:21]
	s_add_u32 s20, s14, s10
	s_addc_u32 s21, s15, s11
	global_load_dwordx4 v[12:15], v173, s[20:21] offset:16
	global_load_dwordx4 v[16:19], v173, s[20:21]
	s_add_u32 s20, s16, s10
	s_addc_u32 s21, s17, s11
	global_load_dwordx4 v[20:23], v173, s[20:21] offset:16
	global_load_dwordx4 v[24:27], v173, s[20:21]
	s_add_u32 s20, s18, s10
	s_addc_u32 s21, s19, s11
	global_load_dwordx4 v[28:31], v173, s[20:21] offset:16
	global_load_dwordx4 v[32:35], v173, s[20:21]
	s_add_u32 s10, s10, 32
	s_addc_u32 s11, s11, 0
	s_waitcnt vmcnt(8)
	v_mov_b32_e32 v72, v44
	v_mov_b32_e32 v44, v46
	v_mov_b32_e32 v46, v48
	v_mov_b32_e32 v74, v52
	v_mov_b32_e32 v52, v54
	v_mov_b32_e32 v73, v60
	v_mov_b32_e32 v60, v45
	v_mov_b32_e32 v45, v62
	v_mov_b32_e32 v75, v68
	v_pk_fma_f32 v[0:1], v[72:73], v[74:75], v[0:1]
	v_mov_b32_e32 v68, v53
	v_pk_fma_f32 v[0:1], v[60:61], v[68:69], v[0:1]
	v_mov_b32_e32 v53, v70
	v_pk_fma_f32 v[0:1], v[44:45], v[52:53], v[0:1]
	v_mov_b32_e32 v62, v47
	v_mov_b32_e32 v70, v55
	v_pk_fma_f32 v[0:1], v[62:63], v[70:71], v[0:1]
	v_mov_b32_e32 v44, v40
	v_mov_b32_e32 v45, v56
	v_mov_b32_e32 v47, v64
	v_pk_fma_f32 v[0:1], v[44:45], v[46:47], v[0:1]
	v_mov_b32_e32 v56, v41
	v_mov_b32_e32 v64, v49
	v_pk_fma_f32 v[0:1], v[56:57], v[64:65], v[0:1]
	v_mov_b32_e32 v40, v42
	v_mov_b32_e32 v41, v58
	v_mov_b32_e32 v44, v50
	v_mov_b32_e32 v45, v66
	v_pk_fma_f32 v[0:1], v[40:41], v[44:45], v[0:1]
	v_mov_b32_e32 v58, v43
	v_mov_b32_e32 v66, v51
	v_pk_fma_f32 v[0:1], v[58:59], v[66:67], v[0:1]
	s_branch .LBB0_477
.Llam_last:
	s_waitcnt vmcnt(0)
	v_mov_b32_e32 v72, v44
	v_mov_b32_e32 v44, v46
	v_mov_b32_e32 v46, v48
	v_mov_b32_e32 v74, v52
	v_mov_b32_e32 v52, v54
	v_mov_b32_e32 v73, v60
	v_mov_b32_e32 v60, v45
	v_mov_b32_e32 v45, v62
	v_mov_b32_e32 v75, v68
	v_pk_fma_f32 v[0:1], v[72:73], v[74:75], v[0:1]
	v_mov_b32_e32 v68, v53
	v_pk_fma_f32 v[0:1], v[60:61], v[68:69], v[0:1]
	v_mov_b32_e32 v53, v70
	v_pk_fma_f32 v[0:1], v[44:45], v[52:53], v[0:1]
	v_mov_b32_e32 v62, v47
	v_mov_b32_e32 v70, v55
	v_pk_fma_f32 v[0:1], v[62:63], v[70:71], v[0:1]
	v_mov_b32_e32 v44, v40
	v_mov_b32_e32 v45, v56
	v_mov_b32_e32 v47, v64
	v_pk_fma_f32 v[0:1], v[44:45], v[46:47], v[0:1]
	v_mov_b32_e32 v56, v41
	v_mov_b32_e32 v64, v49
	v_pk_fma_f32 v[0:1], v[56:57], v[64:65], v[0:1]
	v_mov_b32_e32 v40, v42
	v_mov_b32_e32 v41, v58
	v_mov_b32_e32 v44, v50
	v_mov_b32_e32 v45, v66
	v_pk_fma_f32 v[0:1], v[40:41], v[44:45], v[0:1]
	v_mov_b32_e32 v58, v43
	v_mov_b32_e32 v66, v51
	v_pk_fma_f32 v[0:1], v[58:59], v[66:67], v[0:1]
	v_readlane_b32 s10, v252, 2
	v_readlane_b32 s11, v252, 3
	s_mov_b32 s34, 9
	s_and_b64 vcc, exec, s[10:11]
	s_cbranch_vccz .LBB0_480
	v_readlane_b32 s34, v252, 36
